# v71 plus map-1 epilogue issues global stash loads first and waits only on LDS pieces before combining
# speedup vs baseline: 1.0039x; 1.0007x over previous
; __device__ __forceinline__ float hsum(float v) { auto rr = __builtin_amdgcn_permlane32_swap(__float_as_uint(v), __float_as_uint(v), false, false); return __uint_as_float(rr[0]) + __uint_as_float(rr[1]); }
; __device__ __forceinline__ void da_unit(LAS unsigned char* lds, const AttnP& P, int seqbase, int S, int h, int qb, float lam) {
;     ...
;             const float inv = lam / hsum(l);
; #pragma unroll
;             for (int db = 0; db < 4; ++db)
; #pragma unroll
;                 for (int g = 0; g < 4; ++g) {
;                     const f32x4 st = stash[db * 4 + g];
; #pragma unroll
;                     for (int e = 0; e < 4; ++e) { const float a = st[e] - o[db][4 * g + e] * inv; o[db][4 * g + e] = a; ss += a * a; }
;                 }
.LBB0_450:
	v_mov_b32_e32 v2, v151
	s_and_b64 vcc, exec, s[58:59]
	v_lshrrev_b32_e32 v3, 6, v2
	v_and_b32_e32 v2, 63, v2
	v_lshlrev_b32_e32 v3, 14, v3
	v_lshl_or_b32 v246, v2, 4, v3
	v_add_u32_e32 v247, 0x1000, v246
	v_add_u32_e32 v248, 0x2000, v246
	v_add_u32_e32 v249, 0x3000, v246
	v_lshlrev_b32_e32 v3, 4, v151
	v_add_u32_e32 v2, 0x18000, v3
	v_add_u32_e32 v3, 0x1c700, v3
	s_cbranch_vccz .LBB0_452
	global_load_dwordx4 v[98:101], v247, s[20:21] offset:3072
	global_load_dwordx4 v[102:105], v248, s[20:21] offset:0
	global_load_dwordx4 v[132:135], v248, s[20:21] offset:1024
	global_load_dwordx4 v[136:139], v248, s[20:21] offset:2048
	global_load_dwordx4 v[140:143], v248, s[20:21] offset:3072
	global_load_dwordx4 v[144:147], v249, s[20:21] offset:3072
	global_load_dwordx4 v[160:163], v249, s[20:21] offset:2048
	global_load_dwordx4 v[164:167], v249, s[20:21] offset:1024
	global_load_dwordx4 v[168:171], v249, s[20:21] offset:0
	ds_read_b128 v[4:7], v2 offset:0
	ds_read_b128 v[8:11], v2 offset:8192
	ds_read_b128 v[12:15], v3 offset:0
	ds_read_b128 v[80:83], v3 offset:8192
	ds_read_b128 v[84:87], v3 offset:16384
	ds_read_b128 v[88:91], v3 offset:24576
	ds_read_b128 v[92:95], v3 offset:32768
	v_mov_b32_e32 v96, v0
	v_mov_b32_e32 v97, v0
	s_nop 1
	v_permlane32_swap_b32_e32 v96, v97
	v_add_f32_e32 v96, v96, v97
	v_div_scale_f32 v97, s[10:11], v96, v96, v211
	v_rcp_f32_e32 v106, v97
	v_div_scale_f32 v107, vcc, v211, v96, v211
	v_fma_f32 v108, -v97, v106, 1.0
	v_fmac_f32_e32 v106, v108, v106
	v_mul_f32_e32 v108, v107, v106
	v_fma_f32 v109, -v97, v108, v107
	v_fmac_f32_e32 v108, v109, v106
	v_fma_f32 v97, -v97, v108, v107
	v_div_fmas_f32 v97, v97, v106, v108
	v_div_fixup_f32 v172, v97, v96, v211
	s_waitcnt lgkmcnt(0)
	v_pk_fma_f32 v[130:131], v[64:65], v[172:173], v[4:5] op_sel_hi:[1,0,1] neg_lo:[1,0,0] neg_hi:[1,0,0]
	v_pk_fma_f32 v[128:129], v[66:67], v[172:173], v[6:7] op_sel_hi:[1,0,1] neg_lo:[1,0,0] neg_hi:[1,0,0]
	s_waitcnt vmcnt(14)
	v_pk_fma_f32 v[126:127], v[68:69], v[172:173], v[8:9] op_sel_hi:[1,0,1] neg_lo:[1,0,0] neg_hi:[1,0,0]
	s_waitcnt vmcnt(12)
	v_pk_fma_f32 v[116:117], v[76:77], v[172:173], v[80:81] op_sel_hi:[1,0,1] neg_lo:[1,0,0] neg_hi:[1,0,0]
	v_pk_mul_f32 v[80:81], v[130:131], v[130:131]
	v_pk_fma_f32 v[114:115], v[78:79], v[172:173], v[82:83] op_sel_hi:[1,0,1] neg_lo:[1,0,0] neg_hi:[1,0,0]
	v_add_f32_e32 v80, v222, v80
	v_pk_mul_f32 v[82:83], v[128:129], v[128:129]
	v_add_f32_e32 v80, v81, v80
	v_add_f32_e32 v80, v82, v80
	s_waitcnt vmcnt(11)
	v_pk_fma_f32 v[118:119], v[48:49], v[172:173], v[84:85] op_sel_hi:[1,0,1] neg_lo:[1,0,0] neg_hi:[1,0,0]
	v_pk_mul_f32 v[84:85], v[126:127], v[126:127]
	v_add_f32_e32 v80, v83, v80
	v_pk_fma_f32 v[124:125], v[70:71], v[172:173], v[10:11] op_sel_hi:[1,0,1] neg_lo:[1,0,0] neg_hi:[1,0,0]
	v_add_f32_e32 v80, v84, v80
	s_waitcnt vmcnt(10)
	v_pk_fma_f32 v[110:111], v[52:53], v[172:173], v[88:89] op_sel_hi:[1,0,1] neg_lo:[1,0,0] neg_hi:[1,0,0]
	v_pk_mul_f32 v[88:89], v[124:125], v[124:125]
	v_add_f32_e32 v80, v85, v80
	v_pk_fma_f32 v[122:123], v[72:73], v[172:173], v[12:13] op_sel_hi:[1,0,1] neg_lo:[1,0,0] neg_hi:[1,0,0]
	v_add_f32_e32 v80, v88, v80
	s_waitcnt vmcnt(9)
	v_pk_fma_f32 v[106:107], v[56:57], v[172:173], v[92:93] op_sel_hi:[1,0,1] neg_lo:[1,0,0] neg_hi:[1,0,0]
	s_waitcnt vmcnt(8)
	v_pk_fma_f32 v[92:93], v[60:61], v[172:173], v[98:99] op_sel_hi:[1,0,1] neg_lo:[1,0,0] neg_hi:[1,0,0]
	v_pk_mul_f32 v[98:99], v[122:123], v[122:123]
	v_add_f32_e32 v80, v89, v80
	v_pk_fma_f32 v[120:121], v[74:75], v[172:173], v[14:15] op_sel_hi:[1,0,1] neg_lo:[1,0,0] neg_hi:[1,0,0]
	v_add_f32_e32 v80, v98, v80
	v_pk_fma_f32 v[108:109], v[54:55], v[172:173], v[90:91] op_sel_hi:[1,0,1] neg_lo:[1,0,0] neg_hi:[1,0,0]
	v_pk_fma_f32 v[90:91], v[62:63], v[172:173], v[100:101] op_sel_hi:[1,0,1] neg_lo:[1,0,0] neg_hi:[1,0,0]
	v_pk_mul_f32 v[100:101], v[120:121], v[120:121]
	v_add_f32_e32 v80, v99, v80
	v_add_f32_e32 v80, v100, v80
	v_pk_fma_f32 v[96:97], v[58:59], v[172:173], v[94:95] op_sel_hi:[1,0,1] neg_lo:[1,0,0] neg_hi:[1,0,0]
	s_waitcnt vmcnt(7)
	v_pk_fma_f32 v[94:95], v[32:33], v[172:173], v[102:103] op_sel_hi:[1,0,1] neg_lo:[1,0,0] neg_hi:[1,0,0]
	v_pk_mul_f32 v[102:103], v[116:117], v[116:117]
	v_add_f32_e32 v80, v101, v80
	v_add_f32_e32 v80, v102, v80
	v_pk_fma_f32 v[112:113], v[50:51], v[172:173], v[86:87] op_sel_hi:[1,0,1] neg_lo:[1,0,0] neg_hi:[1,0,0]
	v_pk_fma_f32 v[86:87], v[34:35], v[172:173], v[104:105] op_sel_hi:[1,0,1] neg_lo:[1,0,0] neg_hi:[1,0,0]
	v_pk_mul_f32 v[104:105], v[114:115], v[114:115]
	v_add_f32_e32 v80, v103, v80
	v_add_f32_e32 v80, v104, v80
	s_waitcnt vmcnt(6)
; __device__ __forceinline__ float hsum(float v) { auto rr = __builtin_amdgcn_permlane32_swap(__float_as_uint(v), __float_as_uint(v), false, false); return __uint_as_float(rr[0]) + __uint_as_float(rr[1]); }
; __device__ __forceinline__ void da_unit(LAS unsigned char* lds, const AttnP& P, int seqbase, int S, int h, int qb, float lam) {
;     ...
;             for (int db = 0; db < 4; ++db)
; #pragma unroll
;                 for (int g = 0; g < 4; ++g) {
;                     const f32x4 st = stash[db * 4 + g];
; #pragma unroll
;                     for (int e = 0; e < 4; ++e) { const float a = st[e] - o[db][4 * g + e] * inv; o[db][4 * g + e] = a; ss += a * a; }
;                 }
;         }
;     }
;     ss = hsum(ss);
	v_pk_fma_f32 v[14:15], v[36:37], v[172:173], v[132:133] op_sel_hi:[1,0,1] neg_lo:[1,0,0] neg_hi:[1,0,0]
	v_pk_mul_f32 v[132:133], v[118:119], v[118:119]
	v_add_f32_e32 v80, v105, v80
	v_add_f32_e32 v80, v132, v80
	v_pk_fma_f32 v[12:13], v[38:39], v[172:173], v[134:135] op_sel_hi:[1,0,1] neg_lo:[1,0,0] neg_hi:[1,0,0]
	v_pk_mul_f32 v[134:135], v[112:113], v[112:113]
	v_add_f32_e32 v80, v133, v80
	v_add_f32_e32 v80, v134, v80
	s_waitcnt vmcnt(5)
	v_pk_fma_f32 v[10:11], v[40:41], v[172:173], v[136:137] op_sel_hi:[1,0,1] neg_lo:[1,0,0] neg_hi:[1,0,0]
	v_pk_mul_f32 v[136:137], v[110:111], v[110:111]
	v_add_f32_e32 v80, v135, v80
	v_add_f32_e32 v80, v136, v80
	v_pk_fma_f32 v[8:9], v[42:43], v[172:173], v[138:139] op_sel_hi:[1,0,1] neg_lo:[1,0,0] neg_hi:[1,0,0]
	v_pk_mul_f32 v[138:139], v[108:109], v[108:109]
	v_add_f32_e32 v80, v137, v80
	v_add_f32_e32 v80, v138, v80
	s_waitcnt vmcnt(4)
	v_pk_fma_f32 v[6:7], v[44:45], v[172:173], v[140:141] op_sel_hi:[1,0,1] neg_lo:[1,0,0] neg_hi:[1,0,0]
	v_pk_mul_f32 v[140:141], v[106:107], v[106:107]
	v_add_f32_e32 v80, v139, v80
	v_add_f32_e32 v80, v140, v80
	v_pk_fma_f32 v[4:5], v[46:47], v[172:173], v[142:143] op_sel_hi:[1,0,1] neg_lo:[1,0,0] neg_hi:[1,0,0]
	v_pk_mul_f32 v[142:143], v[96:97], v[96:97]
	v_add_f32_e32 v80, v141, v80
	v_add_f32_e32 v80, v142, v80
	v_pk_mul_f32 v[174:175], v[92:93], v[92:93]
	v_add_f32_e32 v80, v143, v80
	v_add_f32_e32 v80, v174, v80
	v_pk_mul_f32 v[176:177], v[90:91], v[90:91]
	v_add_f32_e32 v80, v175, v80
	v_add_f32_e32 v80, v176, v80
	v_pk_mul_f32 v[178:179], v[94:95], v[94:95]
	v_add_f32_e32 v80, v177, v80
	v_add_f32_e32 v80, v178, v80
	v_pk_mul_f32 v[180:181], v[86:87], v[86:87]
	v_add_f32_e32 v80, v179, v80
	v_add_f32_e32 v80, v180, v80
	v_pk_mul_f32 v[182:183], v[14:15], v[14:15]
	v_add_f32_e32 v80, v181, v80
	v_add_f32_e32 v80, v182, v80
	v_pk_mul_f32 v[184:185], v[12:13], v[12:13]
	v_add_f32_e32 v80, v183, v80
	v_add_f32_e32 v80, v184, v80
	v_pk_mul_f32 v[186:187], v[10:11], v[10:11]
	v_add_f32_e32 v80, v185, v80
	v_add_f32_e32 v80, v186, v80
	v_pk_mul_f32 v[188:189], v[8:9], v[8:9]
	v_add_f32_e32 v80, v187, v80
	v_add_f32_e32 v80, v188, v80
	v_pk_mul_f32 v[190:191], v[6:7], v[6:7]
	v_add_f32_e32 v80, v189, v80
	v_add_f32_e32 v80, v190, v80
	v_add_f32_e32 v82, v191, v80
	v_pk_mul_f32 v[80:81], v[4:5], v[4:5]
	s_waitcnt vmcnt(0)
	v_pk_fma_f32 v[102:103], v[16:17], v[172:173], v[168:169] op_sel_hi:[1,0,1] neg_lo:[1,0,0] neg_hi:[1,0,0]
	v_add_f32_e32 v80, v80, v82
	v_add_f32_e32 v82, v81, v80
	v_pk_mul_f32 v[80:81], v[102:103], v[102:103]
	v_pk_fma_f32 v[104:105], v[18:19], v[172:173], v[170:171] op_sel_hi:[1,0,1] neg_lo:[1,0,0] neg_hi:[1,0,0]
	v_add_f32_e32 v80, v80, v82
	v_add_f32_e32 v82, v81, v80
	v_pk_mul_f32 v[80:81], v[104:105], v[104:105]
	v_pk_fma_f32 v[98:99], v[20:21], v[172:173], v[164:165] op_sel_hi:[1,0,1] neg_lo:[1,0,0] neg_hi:[1,0,0]
	v_add_f32_e32 v80, v80, v82
	v_add_f32_e32 v82, v81, v80
	v_pk_mul_f32 v[80:81], v[98:99], v[98:99]
	v_pk_fma_f32 v[100:101], v[22:23], v[172:173], v[166:167] op_sel_hi:[1,0,1] neg_lo:[1,0,0] neg_hi:[1,0,0]
	v_add_f32_e32 v80, v80, v82
	v_add_f32_e32 v82, v81, v80
	v_pk_mul_f32 v[80:81], v[100:101], v[100:101]
	v_pk_fma_f32 v[88:89], v[24:25], v[172:173], v[160:161] op_sel_hi:[1,0,1] neg_lo:[1,0,0] neg_hi:[1,0,0]
	v_add_f32_e32 v80, v80, v82
	v_add_f32_e32 v82, v81, v80
	v_pk_mul_f32 v[80:81], v[88:89], v[88:89]
	v_pk_fma_f32 v[84:85], v[26:27], v[172:173], v[162:163] op_sel_hi:[1,0,1] neg_lo:[1,0,0] neg_hi:[1,0,0]
	v_add_f32_e32 v80, v80, v82
	v_add_f32_e32 v82, v81, v80
	v_pk_mul_f32 v[80:81], v[84:85], v[84:85]
	s_nop 0
	v_add_f32_e32 v80, v80, v82
	v_add_f32_e32 v132, v81, v80
	v_pk_fma_f32 v[80:81], v[28:29], v[172:173], v[144:145] op_sel_hi:[1,0,1] neg_lo:[1,0,0] neg_hi:[1,0,0]
	s_nop 0
	v_pk_mul_f32 v[82:83], v[80:81], v[80:81]
	s_nop 0
	v_add_f32_e32 v82, v82, v132
	v_add_f32_e32 v134, v83, v82
	v_pk_fma_f32 v[82:83], v[30:31], v[172:173], v[146:147] op_sel_hi:[1,0,1] neg_lo:[1,0,0] neg_hi:[1,0,0]
	s_nop 0
	v_pk_mul_f32 v[132:133], v[82:83], v[82:83]
	s_nop 0
	v_add_f32_e32 v132, v132, v134
	v_add_f32_e32 v132, v133, v132
	s_cbranch_execz .LBB0_453
	s_branch .LBB0_454
